# streaming (nt) cache policy on the once-read residual loads of the last GEMM phase epilogue, stacked on v82
# speedup vs baseline: 1.0028x; 1.0028x over previous
; __device__ __forceinline__ float bf2f(unsigned b) { return __uint_as_float(b << 16); }
; #define EPI_GET(dst, ai, bj, m, s) do { _Pragma("unroll") for (int e_ = 0; e_ < 4; ++e_) { (dst)[e_] = acc[ai][bj][m][0][e_] * (s); (dst)[4 + e_] = acc[ai][bj][m][1][e_] * (s); } } while (0)
;     __device__ __forceinline__ void row(const f32x4 (&acc)[2][2][4][2], int ai, int m, int r, int rl, bool samp, int c8, int fq, const float* a, const float* b) const {
;         float lo[8], hi[8]; EPI_GET(lo, ai, 0, m, 1.f); EPI_GET(hi, ai, 1, m, 1.f);
;         float s2 = 0.f;
; #pragma unroll
;         for (int e = 0; e < 8; ++e) { lo[e] += a[e]; hi[e] += b[e]; s2 += lo[e] * lo[e] + hi[e] * hi[e]; }
;         if (dstP) { float* dp = (samp ? dstS : dstP) + (size_t)rl * 1024 + c8; store8_f32(dp, lo); store8_f32(dp + 128, hi); }
;         if (dstB) { store8_bf16(dstB + (size_t)r * 1024 + c8, lo); store8_bf16(dstB + (size_t)r * 1024 + c8 + 128, hi); }
;         if (ss) { s2 += __shfl_xor(s2, 16); s2 += __shfl_xor(s2, 32); if (fq == 0) atomicAdd(ss + r, s2); }
;     }
;     __device__ __forceinline__ void operator()(const f32x4 (&acc)[2][2][4][2], const Unit& u, int wr, int wc, int fr, int fq) const {
;         const bool samp = (u.pm >= 64); const int c8 = u.pn * 256 + wc * 32 + 8 * fq;
;         if (resB) {
; #pragma unroll
;             for (int ai = 0; ai < 2; ++ai) {
;                 u32x4 ra[4], rb[4];
; #pragma unroll
;                 for (int m = 0; m < 4; ++m) { const int r = EPI_ROWS(ai, m); ra[m] = *(const u32x4*)(resB + (size_t)r * 1024 + c8); rb[m] = *(const u32x4*)(resB + (size_t)r * 1024 + c8 + 128); }
; #pragma unroll
;                 for (int m = 0; m < 4; ++m) { const int r = EPI_ROWS(ai, m); const int rl = samp ? r - MP : r; float a[8], b[8];
;                     const u32x4 wa = ra[m], wb = rb[m];
;                     a[0] = bf2f(wa.x & 0xffffu); a[1] = bf2f(wa.x >> 16); a[2] = bf2f(wa.y & 0xffffu); a[3] = bf2f(wa.y >> 16); a[4] = bf2f(wa.z & 0xffffu); a[5] = bf2f(wa.z >> 16); a[6] = bf2f(wa.w & 0xffffu); a[7] = bf2f(wa.w >> 16);
;                     b[0] = bf2f(wb.x & 0xffffu); b[1] = bf2f(wb.x >> 16); b[2] = bf2f(wb.y & 0xffffu); b[3] = bf2f(wb.y >> 16); b[4] = bf2f(wb.z & 0xffffu); b[5] = bf2f(wb.z >> 16); b[6] = bf2f(wb.w & 0xffffu); b[7] = bf2f(wb.w >> 16);
;                     row(acc, ai, m, r, rl, samp, c8, fq, a, b); }
.LBB0_3619:
	s_andn2_b64 vcc, exec, s[16:17]
	s_cbranch_vccnz .LBB0_3621
	v_lshl_add_u32 v146, s46, 8, v154
	v_lshl_add_u32 v144, s45, 8, v152
	v_ashrrev_i32_e32 v147, 31, v146
	v_ashrrev_i32_e32 v145, 31, v144
	v_lshl_add_u64 v[148:149], v[146:147], 1, s[6:7]
	v_lshlrev_b64 v[150:151], 11, v[144:145]
	v_or_b32_e32 v182, 16, v144
	v_lshl_add_u64 v[150:151], v[148:149], 0, v[150:151]
	v_ashrrev_i32_e32 v183, 31, v182
	global_load_dwordx4 v[158:161], v[150:151], off nt
	global_load_dwordx4 v[162:165], v[150:151], off offset:256 nt
	v_lshlrev_b64 v[150:151], 11, v[182:183]
	v_lshl_add_u64 v[150:151], v[148:149], 0, v[150:151]
	global_load_dwordx4 v[166:169], v[150:151], off nt
	global_load_dwordx4 v[170:173], v[150:151], off offset:256 nt
	v_or_b32_e32 v190, 32, v144
	v_ashrrev_i32_e32 v191, 31, v190
	v_lshlrev_b64 v[174:175], 11, v[190:191]
	v_lshl_add_u64 v[178:179], v[148:149], 0, v[174:175]
	global_load_dwordx4 v[174:177], v[178:179], off offset:256 nt
	s_nop 0
	global_load_dwordx4 v[178:181], v[178:179], off nt
	s_cmp_gt_i32 s45, 63
	v_or_b32_e32 v150, 48, v144
	v_add_u32_e32 v145, 0xffffc000, v144
	v_add_u32_e32 v183, 0xffffc010, v144
	v_ashrrev_i32_e32 v151, 31, v150
	s_cselect_b64 vcc, -1, 0
	v_cndmask_b32_e32 v184, v144, v145, vcc
	v_cndmask_b32_e32 v182, v182, v183, vcc
	v_lshlrev_b64 v[186:187], 11, v[150:151]
	v_ashrrev_i32_e32 v185, 31, v184
	v_ashrrev_i32_e32 v183, 31, v182
	v_lshl_add_u64 v[186:187], v[148:149], 0, v[186:187]
	v_lshlrev_b64 v[192:193], 12, v[184:185]
	v_lshlrev_b64 v[194:195], 12, v[182:183]
	global_load_dwordx4 v[182:185], v[186:187], off offset:256 nt
	s_nop 0
	global_load_dwordx4 v[186:189], v[186:187], off nt
	s_and_b64 s[20:21], vcc, exec
	v_readlane_b32 s20, v250, 0
	v_readlane_b32 s21, v250, 1
	v_readlane_b32 s22, v250, 2
	v_readlane_b32 s23, v250, 3
	s_cselect_b32 s21, s9, s23
	s_cselect_b32 s20, s8, s22
	v_lshlrev_b64 v[146:147], 2, v[146:147]
	v_lshl_add_u64 v[192:193], s[20:21], 0, v[192:193]
	v_lshl_add_u64 v[192:193], v[192:193], 0, v[146:147]
	v_lshl_add_u64 v[194:195], s[20:21], 0, v[194:195]
	v_lshl_add_u64 v[194:195], v[194:195], 0, v[146:147]
	v_readlane_b32 s24, v250, 4
	v_readlane_b32 s25, v250, 5
	v_readlane_b32 s26, v250, 6
	v_readlane_b32 s27, v250, 7
	s_waitcnt vmcnt(0)
	v_lshlrev_b32_e32 v198, 16, v158
	v_and_b32_e32 v199, 0xffff0000, v158
	v_lshlrev_b32_e32 v158, 16, v159
	v_and_b32_e32 v159, 0xffff0000, v159
	v_lshlrev_b32_e32 v200, 16, v164
	v_and_b32_e32 v201, 0xffff0000, v164
	v_lshlrev_b32_e32 v196, 16, v160
	v_and_b32_e32 v197, 0xffff0000, v160
	v_lshlrev_b32_e32 v160, 16, v161
	v_and_b32_e32 v161, 0xffff0000, v161
	v_lshlrev_b32_e32 v164, 16, v165
	v_and_b32_e32 v165, 0xffff0000, v165
	v_lshlrev_b32_e32 v202, 16, v162
	v_and_b32_e32 v203, 0xffff0000, v162
	v_lshlrev_b32_e32 v162, 16, v163
	v_and_b32_e32 v163, 0xffff0000, v163
	v_pk_add_f32 v[124:125], v[124:125], v[198:199]
	v_pk_add_f32 v[126:127], v[126:127], v[158:159]
	v_pk_add_f32 v[112:113], v[112:113], v[200:201]
	v_pk_add_f32 v[120:121], v[120:121], v[196:197]
	v_pk_add_f32 v[122:123], v[122:123], v[160:161]
	v_pk_add_f32 v[114:115], v[114:115], v[164:165]
	v_pk_add_f32 v[116:117], v[116:117], v[202:203]
	v_pk_add_f32 v[118:119], v[118:119], v[162:163]
	global_store_dwordx4 v[192:193], v[124:127], off
	global_store_dwordx4 v[192:193], v[120:123], off offset:16
	global_store_dwordx4 v[192:193], v[116:119], off offset:512
	global_store_dwordx4 v[192:193], v[112:115], off offset:528
	v_lshlrev_b32_e32 v162, 16, v166
	v_and_b32_e32 v163, 0xffff0000, v166
	v_lshlrev_b32_e32 v112, 16, v173
	v_and_b32_e32 v113, 0xffff0000, v173
	v_pk_add_f32 v[102:103], v[102:103], v[112:113]
	v_lshlrev_b32_e32 v112, 16, v170
	v_and_b32_e32 v113, 0xffff0000, v170
	v_lshlrev_b32_e32 v164, 16, v167
	v_and_b32_e32 v165, 0xffff0000, v167
	v_pk_add_f32 v[96:97], v[96:97], v[112:113]
	v_lshlrev_b32_e32 v112, 16, v171
	v_and_b32_e32 v113, 0xffff0000, v171
	v_lshlrev_b32_e32 v158, 16, v168
	v_and_b32_e32 v159, 0xffff0000, v168
	v_lshlrev_b32_e32 v160, 16, v169
	v_and_b32_e32 v161, 0xffff0000, v169
	v_lshlrev_b32_e32 v166, 16, v172
	v_and_b32_e32 v167, 0xffff0000, v172
	v_pk_add_f32 v[108:109], v[108:109], v[162:163]
	v_pk_add_f32 v[110:111], v[110:111], v[164:165]
	v_pk_add_f32 v[98:99], v[98:99], v[112:113]
	v_pk_add_f32 v[104:105], v[104:105], v[158:159]
	v_pk_add_f32 v[106:107], v[106:107], v[160:161]
	v_pk_add_f32 v[100:101], v[100:101], v[166:167]
	global_store_dwordx4 v[194:195], v[108:111], off
	global_store_dwordx4 v[194:195], v[104:107], off offset:16
	global_store_dwordx4 v[194:195], v[96:99], off offset:512
	global_store_dwordx4 v[194:195], v[100:103], off offset:528
	s_nop 0
	v_lshlrev_b32_e32 v98, 16, v180
	v_and_b32_e32 v99, 0xffff0000, v180
	v_pk_add_f32 v[92:93], v[92:93], v[98:99]
	v_lshlrev_b32_e32 v98, 16, v181
	v_and_b32_e32 v99, 0xffff0000, v181
	v_pk_add_f32 v[94:95], v[94:95], v[98:99]
	v_lshlrev_b32_e32 v98, 16, v178
	v_and_b32_e32 v99, 0xffff0000, v178
	v_add_u32_e32 v96, 0xffffc020, v144
	v_pk_add_f32 v[88:89], v[88:89], v[98:99]
	v_lshlrev_b32_e32 v98, 16, v179
	v_and_b32_e32 v99, 0xffff0000, v179
	v_cndmask_b32_e32 v96, v190, v96, vcc
	v_pk_add_f32 v[90:91], v[90:91], v[98:99]
	v_lshlrev_b32_e32 v98, 16, v176
	v_and_b32_e32 v99, 0xffff0000, v176
	v_ashrrev_i32_e32 v97, 31, v96
	v_pk_add_f32 v[84:85], v[84:85], v[98:99]
	v_lshlrev_b32_e32 v98, 16, v177
	v_and_b32_e32 v99, 0xffff0000, v177
	v_lshlrev_b64 v[96:97], 12, v[96:97]
	v_pk_add_f32 v[86:87], v[86:87], v[98:99]
	v_lshlrev_b32_e32 v98, 16, v174
	v_and_b32_e32 v99, 0xffff0000, v174
	v_lshl_add_u64 v[96:97], s[20:21], 0, v[96:97]
	v_pk_add_f32 v[80:81], v[80:81], v[98:99]
; __device__ __forceinline__ float bf2f(unsigned b) { return __uint_as_float(b << 16); }
; #define EPI_GET(dst, ai, bj, m, s) do { _Pragma("unroll") for (int e_ = 0; e_ < 4; ++e_) { (dst)[e_] = acc[ai][bj][m][0][e_] * (s); (dst)[4 + e_] = acc[ai][bj][m][1][e_] * (s); } } while (0)
;     __device__ __forceinline__ void row(const f32x4 (&acc)[2][2][4][2], int ai, int m, int r, int rl, bool samp, int c8, int fq, const float* a, const float* b) const {
;         float lo[8], hi[8]; EPI_GET(lo, ai, 0, m, 1.f); EPI_GET(hi, ai, 1, m, 1.f);
;         float s2 = 0.f;
; #pragma unroll
;         for (int e = 0; e < 8; ++e) { lo[e] += a[e]; hi[e] += b[e]; s2 += lo[e] * lo[e] + hi[e] * hi[e]; }
;         if (dstP) { float* dp = (samp ? dstS : dstP) + (size_t)rl * 1024 + c8; store8_f32(dp, lo); store8_f32(dp + 128, hi); }
;         if (dstB) { store8_bf16(dstB + (size_t)r * 1024 + c8, lo); store8_bf16(dstB + (size_t)r * 1024 + c8 + 128, hi); }
;         if (ss) { s2 += __shfl_xor(s2, 16); s2 += __shfl_xor(s2, 32); if (fq == 0) atomicAdd(ss + r, s2); }
;     }
;     __device__ __forceinline__ void operator()(const f32x4 (&acc)[2][2][4][2], const Unit& u, int wr, int wc, int fr, int fq) const {
;         const bool samp = (u.pm >= 64); const int c8 = u.pn * 256 + wc * 32 + 8 * fq;
;         if (resB) {
; #pragma unroll
;             for (int ai = 0; ai < 2; ++ai) {
;                 u32x4 ra[4], rb[4];
; #pragma unroll
;                 for (int m = 0; m < 4; ++m) { const int r = EPI_ROWS(ai, m); ra[m] = *(const u32x4*)(resB + (size_t)r * 1024 + c8); rb[m] = *(const u32x4*)(resB + (size_t)r * 1024 + c8 + 128); }
; #pragma unroll
;                 for (int m = 0; m < 4; ++m) { const int r = EPI_ROWS(ai, m); const int rl = samp ? r - MP : r; float a[8], b[8];
;                     const u32x4 wa = ra[m], wb = rb[m];
;                     a[0] = bf2f(wa.x & 0xffffu); a[1] = bf2f(wa.x >> 16); a[2] = bf2f(wa.y & 0xffffu); a[3] = bf2f(wa.y >> 16); a[4] = bf2f(wa.z & 0xffffu); a[5] = bf2f(wa.z >> 16); a[6] = bf2f(wa.w & 0xffffu); a[7] = bf2f(wa.w >> 16);
;                     b[0] = bf2f(wb.x & 0xffffu); b[1] = bf2f(wb.x >> 16); b[2] = bf2f(wb.y & 0xffffu); b[3] = bf2f(wb.y >> 16); b[4] = bf2f(wb.z & 0xffffu); b[5] = bf2f(wb.z >> 16); b[6] = bf2f(wb.w & 0xffffu); b[7] = bf2f(wb.w >> 16);
;                     row(acc, ai, m, r, rl, samp, c8, fq, a, b); }
	v_lshlrev_b32_e32 v98, 16, v175
	v_and_b32_e32 v99, 0xffff0000, v175
	v_lshl_add_u64 v[96:97], v[96:97], 0, v[146:147]
	v_pk_add_f32 v[82:83], v[82:83], v[98:99]
	global_store_dwordx4 v[96:97], v[88:91], off
	global_store_dwordx4 v[96:97], v[92:95], off offset:16
	global_store_dwordx4 v[96:97], v[80:83], off offset:512
	global_store_dwordx4 v[96:97], v[84:87], off offset:528
	v_add_u32_e32 v96, 0x80, v144
	v_lshlrev_b32_e32 v82, 16, v188
	v_and_b32_e32 v83, 0xffff0000, v188
	v_pk_add_f32 v[76:77], v[76:77], v[82:83]
	v_lshlrev_b32_e32 v82, 16, v189
	v_and_b32_e32 v83, 0xffff0000, v189
	v_add_u32_e32 v80, 0xffffc030, v144
	v_pk_add_f32 v[78:79], v[78:79], v[82:83]
	v_lshlrev_b32_e32 v82, 16, v186
	v_and_b32_e32 v83, 0xffff0000, v186
	v_cndmask_b32_e32 v80, v150, v80, vcc
	v_pk_add_f32 v[72:73], v[72:73], v[82:83]
	v_lshlrev_b32_e32 v82, 16, v187
	v_and_b32_e32 v83, 0xffff0000, v187
	v_ashrrev_i32_e32 v81, 31, v80
	v_pk_add_f32 v[74:75], v[74:75], v[82:83]
	v_lshlrev_b32_e32 v82, 16, v184
	v_and_b32_e32 v83, 0xffff0000, v184
	v_lshlrev_b64 v[80:81], 12, v[80:81]
	v_pk_add_f32 v[68:69], v[68:69], v[82:83]
	v_lshlrev_b32_e32 v82, 16, v185
	v_and_b32_e32 v83, 0xffff0000, v185
	v_lshl_add_u64 v[80:81], s[20:21], 0, v[80:81]
	v_pk_add_f32 v[70:71], v[70:71], v[82:83]
	v_lshlrev_b32_e32 v82, 16, v182
	v_and_b32_e32 v83, 0xffff0000, v182
	v_lshl_add_u64 v[80:81], v[80:81], 0, v[146:147]
	v_pk_add_f32 v[64:65], v[64:65], v[82:83]
	v_lshlrev_b32_e32 v82, 16, v183
	v_and_b32_e32 v83, 0xffff0000, v183
	v_ashrrev_i32_e32 v97, 31, v96
	v_pk_add_f32 v[66:67], v[66:67], v[82:83]
	global_store_dwordx4 v[80:81], v[72:75], off
	global_store_dwordx4 v[80:81], v[76:79], off offset:16
	global_store_dwordx4 v[80:81], v[64:67], off offset:512
	global_store_dwordx4 v[80:81], v[68:71], off offset:528
	v_add_u32_e32 v98, 0x90, v144
	v_lshlrev_b64 v[64:65], 11, v[96:97]
	v_lshl_add_u64 v[64:65], v[148:149], 0, v[64:65]
	global_load_dwordx4 v[68:71], v[64:65], off nt
	global_load_dwordx4 v[72:75], v[64:65], off offset:256 nt
	v_ashrrev_i32_e32 v99, 31, v98
	v_lshlrev_b64 v[64:65], 11, v[98:99]
	v_lshl_add_u64 v[64:65], v[148:149], 0, v[64:65]
	global_load_dwordx4 v[76:79], v[64:65], off nt
	global_load_dwordx4 v[80:83], v[64:65], off offset:256 nt
	v_add_u32_e32 v102, 0xa0, v144
	v_ashrrev_i32_e32 v103, 31, v102
	v_lshlrev_b64 v[64:65], 11, v[102:103]
	v_lshl_add_u64 v[64:65], v[148:149], 0, v[64:65]
	global_load_dwordx4 v[84:87], v[64:65], off offset:256 nt
	global_load_dwordx4 v[88:91], v[64:65], off nt
	v_add_u32_e32 v100, 0xb0, v144
	v_ashrrev_i32_e32 v101, 31, v100
	v_lshlrev_b64 v[64:65], 11, v[100:101]
	v_lshl_add_u64 v[104:105], v[148:149], 0, v[64:65]
	global_load_dwordx4 v[64:67], v[104:105], off offset:256 nt
	global_load_dwordx4 v[92:95], v[104:105], off nt
	v_add_u32_e32 v97, 0xffffc080, v144
	v_cndmask_b32_e32 v96, v96, v97, vcc
	v_ashrrev_i32_e32 v97, 31, v96
	v_lshlrev_b64 v[96:97], 12, v[96:97]
	v_lshl_add_u64 v[96:97], s[20:21], 0, v[96:97]
	v_lshl_add_u64 v[96:97], v[96:97], 0, v[146:147]
	s_waitcnt vmcnt(7)
	v_lshlrev_b32_e32 v104, 16, v70
	v_and_b32_e32 v105, 0xffff0000, v70
	v_lshlrev_b32_e32 v70, 16, v71
	v_and_b32_e32 v71, 0xffff0000, v71
	v_pk_add_f32 v[62:63], v[62:63], v[70:71]
	v_lshlrev_b32_e32 v70, 16, v68
	v_and_b32_e32 v71, 0xffff0000, v68
	v_lshlrev_b32_e32 v68, 16, v69
	v_and_b32_e32 v69, 0xffff0000, v69
	v_pk_add_f32 v[58:59], v[58:59], v[68:69]
	s_waitcnt vmcnt(6)
	v_lshlrev_b32_e32 v68, 16, v74
	v_and_b32_e32 v69, 0xffff0000, v74
	v_pk_add_f32 v[52:53], v[52:53], v[68:69]
	v_lshlrev_b32_e32 v68, 16, v75
	v_and_b32_e32 v69, 0xffff0000, v75
	v_pk_add_f32 v[54:55], v[54:55], v[68:69]
	v_lshlrev_b32_e32 v68, 16, v72
	v_and_b32_e32 v69, 0xffff0000, v72
	v_pk_add_f32 v[48:49], v[48:49], v[68:69]
	v_lshlrev_b32_e32 v68, 16, v73
	v_and_b32_e32 v69, 0xffff0000, v73
	v_pk_add_f32 v[56:57], v[56:57], v[70:71]
	v_pk_add_f32 v[50:51], v[50:51], v[68:69]
	v_pk_add_f32 v[60:61], v[60:61], v[104:105]
	global_store_dwordx4 v[96:97], v[56:59], off
	global_store_dwordx4 v[96:97], v[60:63], off offset:16
	global_store_dwordx4 v[96:97], v[48:51], off offset:512
	global_store_dwordx4 v[96:97], v[52:55], off offset:528
	s_waitcnt vmcnt(9)
; __device__ __forceinline__ float bf2f(unsigned b) { return __uint_as_float(b << 16); }
; #define EPI_GET(dst, ai, bj, m, s) do { _Pragma("unroll") for (int e_ = 0; e_ < 4; ++e_) { (dst)[e_] = acc[ai][bj][m][0][e_] * (s); (dst)[4 + e_] = acc[ai][bj][m][1][e_] * (s); } } while (0)
;     __device__ __forceinline__ void row(const f32x4 (&acc)[2][2][4][2], int ai, int m, int r, int rl, bool samp, int c8, int fq, const float* a, const float* b) const {
;         float lo[8], hi[8]; EPI_GET(lo, ai, 0, m, 1.f); EPI_GET(hi, ai, 1, m, 1.f);
;         float s2 = 0.f;
; #pragma unroll
;         for (int e = 0; e < 8; ++e) { lo[e] += a[e]; hi[e] += b[e]; s2 += lo[e] * lo[e] + hi[e] * hi[e]; }
;         if (dstP) { float* dp = (samp ? dstS : dstP) + (size_t)rl * 1024 + c8; store8_f32(dp, lo); store8_f32(dp + 128, hi); }
;         if (dstB) { store8_bf16(dstB + (size_t)r * 1024 + c8, lo); store8_bf16(dstB + (size_t)r * 1024 + c8 + 128, hi); }
;         if (ss) { s2 += __shfl_xor(s2, 16); s2 += __shfl_xor(s2, 32); if (fq == 0) atomicAdd(ss + r, s2); }
;     }
;     __device__ __forceinline__ void operator()(const f32x4 (&acc)[2][2][4][2], const Unit& u, int wr, int wc, int fr, int fq) const {
;         const bool samp = (u.pm >= 64); const int c8 = u.pn * 256 + wc * 32 + 8 * fq;
;         if (resB) {
; #pragma unroll
;             for (int ai = 0; ai < 2; ++ai) {
;                 u32x4 ra[4], rb[4];
; #pragma unroll
;                 for (int m = 0; m < 4; ++m) { const int r = EPI_ROWS(ai, m); ra[m] = *(const u32x4*)(resB + (size_t)r * 1024 + c8); rb[m] = *(const u32x4*)(resB + (size_t)r * 1024 + c8 + 128); }
; #pragma unroll
;                 for (int m = 0; m < 4; ++m) { const int r = EPI_ROWS(ai, m); const int rl = samp ? r - MP : r; float a[8], b[8];
;                     const u32x4 wa = ra[m], wb = rb[m];
;                     a[0] = bf2f(wa.x & 0xffffu); a[1] = bf2f(wa.x >> 16); a[2] = bf2f(wa.y & 0xffffu); a[3] = bf2f(wa.y >> 16); a[4] = bf2f(wa.z & 0xffffu); a[5] = bf2f(wa.z >> 16); a[6] = bf2f(wa.w & 0xffffu); a[7] = bf2f(wa.w >> 16);
;                     b[0] = bf2f(wb.x & 0xffffu); b[1] = bf2f(wb.x >> 16); b[2] = bf2f(wb.y & 0xffffu); b[3] = bf2f(wb.y >> 16); b[4] = bf2f(wb.z & 0xffffu); b[5] = bf2f(wb.z >> 16); b[6] = bf2f(wb.w & 0xffffu); b[7] = bf2f(wb.w >> 16);
;                     row(acc, ai, m, r, rl, samp, c8, fq, a, b); }
	v_lshlrev_b32_e32 v50, 16, v78
	v_and_b32_e32 v51, 0xffff0000, v78
	v_pk_add_f32 v[44:45], v[44:45], v[50:51]
	v_lshlrev_b32_e32 v50, 16, v79
	v_and_b32_e32 v51, 0xffff0000, v79
	v_pk_add_f32 v[46:47], v[46:47], v[50:51]
	v_lshlrev_b32_e32 v50, 16, v76
	v_and_b32_e32 v51, 0xffff0000, v76
	v_add_u32_e32 v48, 0xffffc090, v144
	v_pk_add_f32 v[40:41], v[40:41], v[50:51]
	v_lshlrev_b32_e32 v50, 16, v77
	v_and_b32_e32 v51, 0xffff0000, v77
	v_cndmask_b32_e32 v48, v98, v48, vcc
	v_pk_add_f32 v[42:43], v[42:43], v[50:51]
	s_waitcnt vmcnt(8)
	v_lshlrev_b32_e32 v50, 16, v82
	v_and_b32_e32 v51, 0xffff0000, v82
	v_ashrrev_i32_e32 v49, 31, v48
	v_pk_add_f32 v[36:37], v[36:37], v[50:51]
	v_lshlrev_b32_e32 v50, 16, v83
	v_and_b32_e32 v51, 0xffff0000, v83
	v_lshlrev_b64 v[48:49], 12, v[48:49]
	v_pk_add_f32 v[38:39], v[38:39], v[50:51]
	v_lshlrev_b32_e32 v50, 16, v80
	v_and_b32_e32 v51, 0xffff0000, v80
	v_lshl_add_u64 v[48:49], s[20:21], 0, v[48:49]
	v_pk_add_f32 v[32:33], v[32:33], v[50:51]
	v_lshlrev_b32_e32 v50, 16, v81
	v_and_b32_e32 v51, 0xffff0000, v81
	v_lshl_add_u64 v[48:49], v[48:49], 0, v[146:147]
	v_pk_add_f32 v[34:35], v[34:35], v[50:51]
	global_store_dwordx4 v[48:49], v[40:43], off
	global_store_dwordx4 v[48:49], v[44:47], off offset:16
	global_store_dwordx4 v[48:49], v[32:35], off offset:512
	global_store_dwordx4 v[48:49], v[36:39], off offset:528
	s_waitcnt vmcnt(10)
	v_lshlrev_b32_e32 v34, 16, v90
	v_and_b32_e32 v35, 0xffff0000, v90
	v_pk_add_f32 v[28:29], v[28:29], v[34:35]
	v_lshlrev_b32_e32 v34, 16, v91
	v_and_b32_e32 v35, 0xffff0000, v91
	v_pk_add_f32 v[30:31], v[30:31], v[34:35]
	v_lshlrev_b32_e32 v34, 16, v88
	v_and_b32_e32 v35, 0xffff0000, v88
	v_add_u32_e32 v32, 0xffffc0a0, v144
	v_pk_add_f32 v[24:25], v[24:25], v[34:35]
	v_lshlrev_b32_e32 v34, 16, v89
	v_and_b32_e32 v35, 0xffff0000, v89
	v_cndmask_b32_e32 v32, v102, v32, vcc
	v_pk_add_f32 v[26:27], v[26:27], v[34:35]
	v_lshlrev_b32_e32 v34, 16, v86
	v_and_b32_e32 v35, 0xffff0000, v86
	v_ashrrev_i32_e32 v33, 31, v32
	v_pk_add_f32 v[20:21], v[20:21], v[34:35]
	v_lshlrev_b32_e32 v34, 16, v87
	v_and_b32_e32 v35, 0xffff0000, v87
	v_lshlrev_b64 v[32:33], 12, v[32:33]
	v_pk_add_f32 v[22:23], v[22:23], v[34:35]
	v_lshlrev_b32_e32 v34, 16, v84
	v_and_b32_e32 v35, 0xffff0000, v84
	v_lshl_add_u64 v[32:33], s[20:21], 0, v[32:33]
	v_pk_add_f32 v[16:17], v[16:17], v[34:35]
	v_lshlrev_b32_e32 v34, 16, v85
	v_and_b32_e32 v35, 0xffff0000, v85
	v_lshl_add_u64 v[32:33], v[32:33], 0, v[146:147]
	v_pk_add_f32 v[18:19], v[18:19], v[34:35]
	global_store_dwordx4 v[32:33], v[24:27], off
	global_store_dwordx4 v[32:33], v[28:31], off offset:16
	global_store_dwordx4 v[32:33], v[16:19], off offset:512
	global_store_dwordx4 v[32:33], v[20:23], off offset:528
	s_waitcnt vmcnt(12)
	v_lshlrev_b32_e32 v18, 16, v94
	v_and_b32_e32 v19, 0xffff0000, v94
	v_pk_add_f32 v[12:13], v[12:13], v[18:19]
	v_lshlrev_b32_e32 v18, 16, v95
	v_and_b32_e32 v19, 0xffff0000, v95
	v_add_u32_e32 v16, 0xffffc0b0, v144
	v_pk_add_f32 v[14:15], v[14:15], v[18:19]
	v_lshlrev_b32_e32 v18, 16, v92
	v_and_b32_e32 v19, 0xffff0000, v92
	v_cndmask_b32_e32 v16, v100, v16, vcc
	v_pk_add_f32 v[8:9], v[8:9], v[18:19]
	v_lshlrev_b32_e32 v18, 16, v93
	v_and_b32_e32 v19, 0xffff0000, v93
	v_ashrrev_i32_e32 v17, 31, v16
	v_pk_add_f32 v[10:11], v[10:11], v[18:19]
	v_lshlrev_b32_e32 v18, 16, v66
	v_and_b32_e32 v19, 0xffff0000, v66
	v_lshlrev_b64 v[16:17], 12, v[16:17]
	v_pk_add_f32 v[4:5], v[4:5], v[18:19]
	v_lshlrev_b32_e32 v18, 16, v67
	v_and_b32_e32 v19, 0xffff0000, v67
	v_lshl_add_u64 v[16:17], s[20:21], 0, v[16:17]
	v_pk_add_f32 v[6:7], v[6:7], v[18:19]
	v_lshlrev_b32_e32 v18, 16, v64
	v_and_b32_e32 v19, 0xffff0000, v64
	v_lshl_add_u64 v[16:17], v[16:17], 0, v[146:147]
	v_pk_add_f32 v[0:1], v[0:1], v[18:19]
	v_lshlrev_b32_e32 v18, 16, v65
	v_and_b32_e32 v19, 0xffff0000, v65
	v_pk_add_f32 v[2:3], v[2:3], v[18:19]
	global_store_dwordx4 v[16:17], v[8:11], off
	global_store_dwordx4 v[16:17], v[12:15], off offset:16
	global_store_dwordx4 v[16:17], v[0:3], off offset:512
	global_store_dwordx4 v[16:17], v[4:7], off offset:528
